# v_c7 + GLU phase: the 16 gate workgroups of each XCD prefetch that XCD's GLU-GEMM operands (4 MB YPRE + 1 MB Wglu) into L2 before their gate work
# speedup vs baseline: 1.0060x; 1.0052x over previous
; __device__ __forceinline__ int fresh_lane() { int l; asm volatile("v_mbcnt_lo_u32_b32 %0, -1, 0\n\tv_mbcnt_hi_u32_b32 %0, -1, %0" : "=v"(l)); return l; }
; __device__ __forceinline__ void dn_gate_phase(const float* ODN, const bf16* PROJ, const float* norm_g, bf16* MIX, int G, int wave_s) {
;     int tid_ = wave_s * 64 + fresh_lane(); asm volatile("" : "+v"(tid_)); const int lane = tid_ & 63;
;     const int first = (G >= 256) ? 128 : 0;
;     if ((int)blockIdx.x < first) return;
;     const int gw = ((int)blockIdx.x - first) * 8 + (tid_ >> 6), NGW = (G - first) * 8;
;     const f32x2 g2 = *(const f32x2*)(norm_g + 2 * lane);
.LBB0_1643:
	s_cmpk_gt_i32 s10, 0xff
	v_mbcnt_lo_u32_b32 v0, -1, 0
	v_mbcnt_hi_u32_b32 v0, -1, v0
	s_cselect_b32 s6, 0x80, 0
	v_readlane_b32 s0, v253, 0
	v_add_u32_e32 v0, s89, v0
	s_cmp_lt_i32 s0, s6
	v_readlane_b32 s1, v253, 1
	s_cbranch_scc1 .LBB0_1648
	v_readlane_b32 s100, v253, 0
	v_readlane_b32 s101, v254, 57
	v_mov_b32_e32 v240, s100
	v_and_b32_e32 v241, 7, v240
	v_bfe_u32 v240, v240, 3, 4
	v_lshl_add_u32 v240, v240, 9, v0
	v_lshrrev_b32_e32 v242, 1, v241
	v_and_b32_e32 v241, 1, v241
	v_lshlrev_b32_e32 v242, 22, v242
	v_add_u32_e32 v242, 0x30700000, v242
	v_lshlrev_b32_e32 v241, 20, v241
	v_mov_b32_e32 v243, s101
	v_lshl_add_u32 v241, v243, 21, v241
	v_add_u32_e32 v241, 0x7e00000, v241
	v_mov_b32_e32 v243, v240
	v_lshrrev_b32_e32 v244, 9, v243
	v_mul_u32_u24_e32 v244, 0xcccd, v244
	v_lshrrev_b32_e32 v244, 18, v244
	v_mul_u32_u24_e32 v245, 0xa00, v244
	v_sub_u32_e32 v243, v243, v245
	v_cmp_lt_u32_e32 vcc, 0x7ff, v243
	v_cndmask_b32_e32 v245, v242, v241, vcc
	v_lshl_add_u32 v245, v243, 11, v245
	v_lshl_add_u32 v245, v244, 7, v245
	global_load_dword v250, v245, s[16:17]
	v_add_u32_e32 v243, 0x2000, v240
	v_lshrrev_b32_e32 v244, 9, v243
	v_mul_u32_u24_e32 v244, 0xcccd, v244
	v_lshrrev_b32_e32 v244, 18, v244
	v_mul_u32_u24_e32 v245, 0xa00, v244
	v_sub_u32_e32 v243, v243, v245
	v_cmp_lt_u32_e32 vcc, 0x7ff, v243
	v_cndmask_b32_e32 v245, v242, v241, vcc
	v_lshl_add_u32 v245, v243, 11, v245
	v_lshl_add_u32 v245, v244, 7, v245
	global_load_dword v250, v245, s[16:17]
	v_add_u32_e32 v243, 0x4000, v240
	v_lshrrev_b32_e32 v244, 9, v243
	v_mul_u32_u24_e32 v244, 0xcccd, v244
	v_lshrrev_b32_e32 v244, 18, v244
	v_mul_u32_u24_e32 v245, 0xa00, v244
	v_sub_u32_e32 v243, v243, v245
	v_cmp_lt_u32_e32 vcc, 0x7ff, v243
	v_cndmask_b32_e32 v245, v242, v241, vcc
	v_lshl_add_u32 v245, v243, 11, v245
	v_lshl_add_u32 v245, v244, 7, v245
	global_load_dword v250, v245, s[16:17]
	v_add_u32_e32 v243, 0x6000, v240
	v_lshrrev_b32_e32 v244, 9, v243
	v_mul_u32_u24_e32 v244, 0xcccd, v244
	v_lshrrev_b32_e32 v244, 18, v244
	v_mul_u32_u24_e32 v245, 0xa00, v244
	v_sub_u32_e32 v243, v243, v245
	v_cmp_lt_u32_e32 vcc, 0x7ff, v243
	v_cndmask_b32_e32 v245, v242, v241, vcc
	v_lshl_add_u32 v245, v243, 11, v245
	v_lshl_add_u32 v245, v244, 7, v245
	global_load_dword v250, v245, s[16:17]
	v_add_u32_e32 v243, 0x8000, v240
	v_lshrrev_b32_e32 v244, 9, v243
	v_mul_u32_u24_e32 v244, 0xcccd, v244
	v_lshrrev_b32_e32 v244, 18, v244
	v_mul_u32_u24_e32 v245, 0xa00, v244
	v_sub_u32_e32 v243, v243, v245
	v_cmp_lt_u32_e32 vcc, 0x7ff, v243
	v_cndmask_b32_e32 v245, v242, v241, vcc
	v_lshl_add_u32 v245, v243, 11, v245
	v_lshl_add_u32 v245, v244, 7, v245
	global_load_dword v250, v245, s[16:17]
	v_readlane_b32 s0, v253, 0
	s_sub_i32 s0, s0, s6
	v_ashrrev_i32_e32 v2, 6, v0
	v_lshl_add_u32 v2, s0, 3, v2
	v_readlane_b32 s1, v253, 1
	v_cmp_gt_i32_e32 vcc, s33, v2
	s_and_saveexec_b64 s[0:1], vcc
	s_cbranch_execz .LBB0_1647
	s_load_dwordx2 s[8:9], s[40:41], 0x80
	s_sub_i32 s12, s10, s6
	v_readlane_b32 s6, v254, 57
	s_lshl_b32 s80, s6, 7
	s_lshl_b32 s6, s12, 3
	s_lshl_b64 s[10:11], s[80:81], 2
	s_waitcnt lgkmcnt(0)
	s_add_u32 s8, s8, s10
	v_lshlrev_b32_e32 v3, 3, v0
	s_addc_u32 s9, s9, s11
	v_and_b32_e32 v3, 0x1f8, v3
	global_load_dwordx2 v[4:5], v3, s[8:9]
	v_readlane_b32 s7, v254, 58
	v_ashrrev_i32_e32 v3, 31, v2
	v_and_b32_e32 v0, 63, v0
	v_mad_i64_i32 v[6:7], s[8:9], v2, s74, 0
	v_lshlrev_b32_e32 v12, 2, v0
	s_ashr_i32 s7, s6, 31
	v_lshlrev_b64 v[8:9], 12, v[2:3]
	v_or_b32_e32 v6, v6, v12
	s_mul_i32 s8, s12, 0x18000
	s_mul_hi_i32 s9, s6, 0x3000
	v_lshl_or_b32 v10, v0, 3, v8
	v_mov_b32_e32 v11, v9
	s_lshl_b64 s[10:11], s[6:7], 12
	v_or_b32_e32 v8, v8, v12
	s_mov_b64 s[12:13], 0
